# in-proj sigmoid epilogue: fold -log2e into per-row rstd (f32 math, same ops otherwise)
# baseline (speedup 1.0000x reference)
; __device__ __forceinline__ float sigm(float x) { x = fmaxf(x, -60.f); return __builtin_amdgcn_rcpf(1.f + __expf(-x)); }
; __device__ __forceinline__ u32x4 pack8(const f32x4& a, const f32x4& b) { u32x4 w; w.x = cvt_pk_bf16(a[0], a[1]); w.y = cvt_pk_bf16(a[2], a[3]); w.z = cvt_pk_bf16(b[0], b[1]); w.w = cvt_pk_bf16(b[2], b[3]); return w; }
; __device__ __forceinline__ size_t paddr(int row, int col) { return ((size_t)(col >> 7) * 16384 + (size_t)row) * 128 + (col & 127); }
; __device__ __forceinline__ size_t paddr(int row, int col) { return ((size_t)(col >> 7) * TH + (size_t)row) * 128 + (col & 127); }
;     template <int KIND> __device__ __forceinline__ void body(f32x4 (&acc)[2][2][4][2], const Unit& u, int wr, int wc, int fr, int fq, const Pre& pre) const {
;     ...
; #pragma unroll
;         for (int ai = 0; ai < 2; ++ai)
; #pragma unroll
;             for (int m = 0; m < 4; ++m) rsv[ai][m] = rsqrtf((float)pre.r[ai][m] * (5.9604644775390625e-08f * (1.0f / 2048.0f)) + 1e-6f);
; #pragma unroll
;         for (int ai = 0; ai < 2; ++ai)
; #pragma unroll
;             for (int m = 0; m < 4; ++m) {
;                 const int row = row0 + ai * HALF + m * 16;
;                 const float rs = rsv[ai][m];
; #pragma unroll
;                 for (int bj = 0; bj < 2; ++bj) {
;                     f32x4 v0 = acc[ai][bj][m][0] * rs, v1 = acc[ai][bj][m][1] * rs;
;                     if (KIND == 1) {
; #pragma unroll
;                         for (int j = 0; j < 4; ++j) { v0[j] = fmaxf(__log2f(1.0f - lk[bj][0][j] * sigm(-v0[j])), -120.f); v1[j] = fmaxf(__log2f(1.0f - lk[bj][1][j] * sigm(-v1[j])), -120.f); }
;                     } else if (KIND == 2) {
; #pragma unroll
;                         for (int j = 0; j < 4; ++j) { v0[j] = v0[j] * sigm(v0[j]); v1[j] = v1[j] * sigm(v1[j]); }
;                     } else if (KIND == 3) {
;                         v0 = v0 * 0.08838834764831845f; v1 = v1 * 0.08838834764831845f;
;                     } else if (KIND == 4) {
; #pragma unroll
;                         for (int j = 0; j < 4; ++j) { v0[j] = sigm(v0[j]); v1[j] = sigm(v1[j]); }
;                     }
;                     *(u32x4*)(P + paddr(row, col0 + bj * HALF)) = pack8(v0, v1);
.LBB0_158:
	s_and_b64 vcc, exec, s[6:7]
	v_lshlrev_b32_e32 v188, 1, v152
	s_cbranch_vccz .LBB0_160
	s_waitcnt vmcnt(8)
	v_ffbh_u32_e32 v128, v173
	v_min_u32_e32 v130, 32, v128
	v_lshlrev_b64 v[128:129], v130, v[172:173]
	v_min_u32_e32 v128, 1, v128
	v_or_b32_e32 v128, v129, v128
	v_cvt_f32_u32_e32 v128, v128
	v_sub_u32_e32 v129, 32, v130
	s_mov_b32 s2, 0x358637bd
	s_lshl_b32 s52, s52, 1
	v_ldexp_f32 v129, v128, v129
	v_ffbh_u32_e32 v128, v171
	v_min_u32_e32 v128, 32, v128
	v_lshlrev_b64 v[130:131], v128, v[170:171]
	v_min_u32_e32 v130, 1, v130
	v_or_b32_e32 v130, v131, v130
	v_cvt_f32_u32_e32 v130, v130
	v_sub_u32_e32 v128, 32, v128
	v_or_b32_e32 v142, s23, v153
	v_ashrrev_i32_e32 v143, 31, v142
	v_ldexp_f32 v128, v130, v128
	v_mov_b64_e32 v[130:131], s[2:3]
	v_pk_fma_f32 v[128:129], v[128:129], s[50:51], v[130:131] op_sel_hi:[1,0,0]
	s_nop 0
	v_mul_f32_e32 v132, 0x4b800000, v129
	v_cmp_gt_f32_e64 s[6:7], s84, v129
	v_cmp_gt_f32_e32 vcc, s84, v128
	s_nop 0
	v_cndmask_b32_e64 v129, v129, v132, s[6:7]
	v_rsq_f32_e32 v129, v129
	s_nop 0
	v_mul_f32_e32 v132, 0x45800000, v129
	v_cndmask_b32_e64 v172, v129, v132, s[6:7]
	v_mul_f32_e32 v172, 0xbfb8aa3b, v172
	v_mul_f32_e32 v129, 0x4b800000, v128
	v_cndmask_b32_e32 v128, v128, v129, vcc
	v_rsq_f32_e32 v128, v128
	v_pk_mul_f32 v[122:123], v[172:173], v[122:123] op_sel_hi:[0,1]
	v_pk_mul_f32 v[120:121], v[172:173], v[120:121] op_sel_hi:[0,1]
	v_min_f32_e32 v120, 0x42ad1f97, v120
	v_mul_f32_e32 v129, 0x45800000, v128
	v_cndmask_b32_e32 v170, v128, v129, vcc
	v_mul_f32_e32 v170, 0xbfb8aa3b, v170
	v_ffbh_u32_e32 v128, v169
	v_min_u32_e32 v132, 32, v128
	v_lshlrev_b64 v[128:129], v132, v[168:169]
	v_min_u32_e32 v128, 1, v128
	v_or_b32_e32 v128, v129, v128
	v_cvt_f32_u32_e32 v128, v128
	v_sub_u32_e32 v129, 32, v132
	v_min_f32_e32 v121, 0x42ad1f97, v121
	v_min_f32_e32 v122, 0x42ad1f97, v122
	v_ldexp_f32 v129, v128, v129
	v_ffbh_u32_e32 v128, v167
	v_min_u32_e32 v128, 32, v128
	v_lshlrev_b64 v[132:133], v128, v[166:167]
	v_min_u32_e32 v132, 1, v132
	v_or_b32_e32 v132, v133, v132
	v_cvt_f32_u32_e32 v132, v132
	v_sub_u32_e32 v128, 32, v128
	v_ldexp_f32 v128, v132, v128
	v_pk_fma_f32 v[128:129], v[128:129], s[50:51], v[130:131] op_sel_hi:[1,0,0]
	v_mul_f32_e32 v132, 0x4b800000, v129
	v_cmp_gt_f32_e64 s[6:7], s84, v129
	v_cmp_gt_f32_e32 vcc, s84, v128
	v_exp_f32_e32 v120, v120
	v_cndmask_b32_e64 v129, v129, v132, s[6:7]
	v_rsq_f32_e32 v129, v129
	v_exp_f32_e32 v121, v121
	v_exp_f32_e32 v122, v122
	v_pk_mul_f32 v[126:127], v[172:173], v[126:127] op_sel_hi:[0,1]
	v_mul_f32_e32 v132, 0x45800000, v129
	v_cndmask_b32_e64 v140, v129, v132, s[6:7]
	v_mul_f32_e32 v140, 0xbfb8aa3b, v140
	v_mul_f32_e32 v129, 0x4b800000, v128
	v_cndmask_b32_e32 v128, v128, v129, vcc
	v_rsq_f32_e32 v128, v128
	v_pk_mul_f32 v[124:125], v[172:173], v[124:125] op_sel_hi:[0,1]
	v_add_f32_e32 v120, 1.0, v120
	v_add_f32_e32 v121, 1.0, v121
	v_mul_f32_e32 v129, 0x45800000, v128
	v_cndmask_b32_e32 v138, v128, v129, vcc
	v_mul_f32_e32 v138, 0xbfb8aa3b, v138
	v_ffbh_u32_e32 v128, v165
	v_min_u32_e32 v132, 32, v128
	v_lshlrev_b64 v[128:129], v132, v[164:165]
	v_min_u32_e32 v128, 1, v128
	v_or_b32_e32 v128, v129, v128
	v_cvt_f32_u32_e32 v128, v128
	v_sub_u32_e32 v129, 32, v132
	v_add_f32_e32 v122, 1.0, v122
	v_min_f32_e32 v124, 0x42ad1f97, v124
	v_ldexp_f32 v129, v128, v129
	v_ffbh_u32_e32 v128, v163
	v_min_u32_e32 v128, 32, v128
	v_lshlrev_b64 v[132:133], v128, v[162:163]
	v_min_u32_e32 v132, 1, v132
	v_or_b32_e32 v132, v133, v132
	v_cvt_f32_u32_e32 v132, v132
	v_sub_u32_e32 v128, 32, v128
	v_exp_f32_e32 v124, v124
	v_ldexp_f32 v128, v132, v128
	v_pk_fma_f32 v[128:129], v[128:129], s[50:51], v[130:131] op_sel_hi:[1,0,0]
	v_min_f32_e32 v123, 0x42ad1f97, v123
	v_mul_f32_e32 v132, 0x4b800000, v129
	v_cmp_gt_f32_e64 s[6:7], s84, v129
	v_cmp_gt_f32_e32 vcc, s84, v128
	v_pk_mul_f32 v[114:115], v[172:173], v[114:115] op_sel_hi:[0,1]
	v_cndmask_b32_e64 v129, v129, v132, s[6:7]
	v_rsq_f32_e32 v129, v129
	v_pk_mul_f32 v[112:113], v[172:173], v[112:113] op_sel_hi:[0,1]
	v_min_f32_e32 v112, 0x42ad1f97, v112
	v_mul_f32_e32 v132, 0x45800000, v129
	v_cndmask_b32_e64 v136, v129, v132, s[6:7]
	v_mul_f32_e32 v136, 0xbfb8aa3b, v136
	v_mul_f32_e32 v129, 0x4b800000, v128
	v_cndmask_b32_e32 v128, v128, v129, vcc
	v_rsq_f32_e32 v128, v128
	v_min_f32_e32 v113, 0x42ad1f97, v113
	v_min_f32_e32 v114, 0x42ad1f97, v114
	v_exp_f32_e32 v123, v123
	v_mul_f32_e32 v129, 0x45800000, v128
	v_cndmask_b32_e32 v134, v128, v129, vcc
	v_mul_f32_e32 v134, 0xbfb8aa3b, v134
	v_ffbh_u32_e32 v128, v161
	v_min_u32_e32 v132, 32, v128
	v_lshlrev_b64 v[128:129], v132, v[160:161]
	v_min_u32_e32 v128, 1, v128
	v_or_b32_e32 v128, v129, v128
	v_cvt_f32_u32_e32 v128, v128
	v_sub_u32_e32 v129, 32, v132
	v_ldexp_f32 v129, v128, v129
	v_ffbh_u32_e32 v128, v159
	v_min_u32_e32 v128, 32, v128
	v_lshlrev_b64 v[132:133], v128, v[158:159]
	v_min_u32_e32 v132, 1, v132
	v_or_b32_e32 v132, v133, v132
	v_cvt_f32_u32_e32 v132, v132
	v_sub_u32_e32 v128, 32, v128
	v_exp_f32_e32 v112, v112
	v_ldexp_f32 v128, v132, v128
	v_pk_fma_f32 v[128:129], v[128:129], s[50:51], v[130:131] op_sel_hi:[1,0,0]
	v_exp_f32_e32 v113, v113
	v_mul_f32_e32 v130, 0x4b800000, v129
	v_cmp_gt_f32_e64 s[6:7], s84, v129
	v_cmp_gt_f32_e32 vcc, s84, v128
	v_exp_f32_e32 v114, v114
	v_cndmask_b32_e64 v129, v129, v130, s[6:7]
	v_rsq_f32_e32 v129, v129
	v_add_f32_e32 v124, 1.0, v124
	v_rcp_f32_e32 v124, v124
	v_add_f32_e32 v123, 1.0, v123
	v_mul_f32_e32 v130, 0x45800000, v129
	v_cndmask_b32_e64 v132, v129, v130, s[6:7]
	v_mul_f32_e32 v132, 0xbfb8aa3b, v132
	v_mul_f32_e32 v129, 0x4b800000, v128
	v_cndmask_b32_e32 v128, v128, v129, vcc
	v_rsq_f32_e32 v128, v128
; __device__ __forceinline__ float sigm(float x) { x = fmaxf(x, -60.f); return __builtin_amdgcn_rcpf(1.f + __expf(-x)); }
; __device__ __forceinline__ u32x4 pack8(const f32x4& a, const f32x4& b) { u32x4 w; w.x = cvt_pk_bf16(a[0], a[1]); w.y = cvt_pk_bf16(a[2], a[3]); w.z = cvt_pk_bf16(b[0], b[1]); w.w = cvt_pk_bf16(b[2], b[3]); return w; }
; __device__ __forceinline__ size_t paddr(int row, int col) { return ((size_t)(col >> 7) * 16384 + (size_t)row) * 128 + (col & 127); }
; __device__ __forceinline__ size_t paddr(int row, int col) { return ((size_t)(col >> 7) * TH + (size_t)row) * 128 + (col & 127); }
;     template <int KIND> __device__ __forceinline__ void body(f32x4 (&acc)[2][2][4][2], const Unit& u, int wr, int wc, int fr, int fq, const Pre& pre) const {
;     ...
;             for (int m = 0; m < 4; ++m) rsv[ai][m] = rsqrtf((float)pre.r[ai][m] * (5.9604644775390625e-08f * (1.0f / 2048.0f)) + 1e-6f);
; #pragma unroll
;         for (int ai = 0; ai < 2; ++ai)
; #pragma unroll
;             for (int m = 0; m < 4; ++m) {
;                 const int row = row0 + ai * HALF + m * 16;
;                 const float rs = rsv[ai][m];
; #pragma unroll
;                 for (int bj = 0; bj < 2; ++bj) {
;                     f32x4 v0 = acc[ai][bj][m][0] * rs, v1 = acc[ai][bj][m][1] * rs;
;                     if (KIND == 1) {
; #pragma unroll
;                         for (int j = 0; j < 4; ++j) { v0[j] = fmaxf(__log2f(1.0f - lk[bj][0][j] * sigm(-v0[j])), -120.f); v1[j] = fmaxf(__log2f(1.0f - lk[bj][1][j] * sigm(-v1[j])), -120.f); }
;                     } else if (KIND == 2) {
; #pragma unroll
;                         for (int j = 0; j < 4; ++j) { v0[j] = v0[j] * sigm(v0[j]); v1[j] = v1[j] * sigm(v1[j]); }
;                     } else if (KIND == 3) {
;                         v0 = v0 * 0.08838834764831845f; v1 = v1 * 0.08838834764831845f;
;                     } else if (KIND == 4) {
; #pragma unroll
;                         for (int j = 0; j < 4; ++j) { v0[j] = sigm(v0[j]); v1[j] = sigm(v1[j]); }
;                     }
;                     *(u32x4*)(P + paddr(row, col0 + bj * HALF)) = pack8(v0, v1);
	s_lshl_b64 s[6:7], s[52:53], 22
	s_add_u32 s6, s16, s6
	v_lshlrev_b64 v[130:131], 8, v[142:143]
	v_mul_f32_e32 v129, 0x45800000, v128
	v_cndmask_b32_e32 v128, v128, v129, vcc
	v_mul_f32_e32 v128, 0xbfb8aa3b, v128
	v_rcp_f32_e32 v129, v120
	v_min_f32_e32 v120, 0x42ad1f97, v125
	v_rcp_f32_e32 v125, v121
	v_min_f32_e32 v121, 0x42ad1f97, v126
	v_rcp_f32_e32 v126, v122
	v_min_f32_e32 v122, 0x42ad1f97, v127
	v_exp_f32_e32 v120, v120
	v_exp_f32_e32 v121, v121
	v_exp_f32_e32 v122, v122
	s_addc_u32 s7, s17, s7
	v_add_f32_e32 v120, 1.0, v120
	v_add_f32_e32 v121, 1.0, v121
	v_add_f32_e32 v122, 1.0, v122
	v_rcp_f32_e32 v120, v120
	v_rcp_f32_e32 v121, v121
	v_rcp_f32_e32 v122, v122
	v_cvt_pk_bf16_f32 v120, v124, v120
	v_cvt_pk_bf16_f32 v121, v121, v122
	v_cvt_pk_bf16_f32 v122, v129, v125
	v_lshl_add_u64 v[124:125], s[6:7], 0, v[130:131]
	v_rcp_f32_e32 v123, v123
	v_lshl_add_u64 v[124:125], v[124:125], 0, v[188:189]
	v_pk_mul_f32 v[118:119], v[172:173], v[118:119] op_sel_hi:[0,1]
	v_pk_mul_f32 v[116:117], v[172:173], v[116:117] op_sel_hi:[0,1]
	v_add_f32_e32 v112, 1.0, v112
	v_add_f32_e32 v113, 1.0, v113
	v_add_f32_e32 v114, 1.0, v114
	v_cvt_pk_bf16_f32 v123, v126, v123
	global_store_dwordx4 v[124:125], v[120:123], off
	v_min_f32_e32 v116, 0x42ad1f97, v116
	v_rcp_f32_e32 v120, v112
	v_min_f32_e32 v112, 0x42ad1f97, v117
	v_rcp_f32_e32 v117, v113
	v_min_f32_e32 v113, 0x42ad1f97, v118
	v_rcp_f32_e32 v118, v114
	v_min_f32_e32 v114, 0x42ad1f97, v119
	v_exp_f32_e32 v116, v116
	v_exp_f32_e32 v112, v112
	v_exp_f32_e32 v113, v113
	v_exp_f32_e32 v114, v114
	v_min_f32_e32 v115, 0x42ad1f97, v115
	v_pk_mul_f32 v[106:107], v[170:171], v[106:107] op_sel_hi:[0,1]
	v_pk_mul_f32 v[104:105], v[170:171], v[104:105] op_sel_hi:[0,1]
	v_min_f32_e32 v104, 0x42ad1f97, v104
	v_min_f32_e32 v105, 0x42ad1f97, v105
	v_min_f32_e32 v106, 0x42ad1f97, v106
	v_exp_f32_e32 v115, v115
	s_or_b32 s52, s52, 1
	s_lshl_b64 s[8:9], s[52:53], 22
	v_exp_f32_e32 v104, v104
	v_exp_f32_e32 v105, v105
	v_exp_f32_e32 v106, v106
	v_add_f32_e32 v116, 1.0, v116
	v_add_f32_e32 v112, 1.0, v112
	v_add_f32_e32 v113, 1.0, v113
	v_add_f32_e32 v114, 1.0, v114
	s_add_u32 s30, s16, s8
	v_rcp_f32_e32 v116, v116
	v_rcp_f32_e32 v112, v112
	v_rcp_f32_e32 v113, v113
	v_rcp_f32_e32 v114, v114
	s_addc_u32 s31, s17, s9
	v_add_f32_e32 v115, 1.0, v115
	v_cvt_pk_bf16_f32 v112, v116, v112
	v_cvt_pk_bf16_f32 v113, v113, v114
	v_cvt_pk_bf16_f32 v114, v120, v117
	v_lshl_add_u64 v[116:117], s[30:31], 0, v[130:131]
	v_rcp_f32_e32 v115, v115
	v_lshl_add_u64 v[116:117], v[116:117], 0, v[188:189]
	v_pk_mul_f32 v[110:111], v[170:171], v[110:111] op_sel_hi:[0,1]
	v_pk_mul_f32 v[108:109], v[170:171], v[108:109] op_sel_hi:[0,1]
	v_add_f32_e32 v104, 1.0, v104
	v_add_f32_e32 v105, 1.0, v105
	v_add_f32_e32 v106, 1.0, v106
	v_cvt_pk_bf16_f32 v115, v118, v115
	global_store_dwordx4 v[116:117], v[112:115], off
	v_min_f32_e32 v108, 0x42ad1f97, v108
	v_rcp_f32_e32 v114, v104
	v_min_f32_e32 v104, 0x42ad1f97, v109
	v_rcp_f32_e32 v109, v105
	v_min_f32_e32 v105, 0x42ad1f97, v110
	v_rcp_f32_e32 v110, v106
	v_min_f32_e32 v106, 0x42ad1f97, v111
	v_exp_f32_e32 v108, v108
	v_exp_f32_e32 v104, v104
	v_exp_f32_e32 v105, v105
	v_exp_f32_e32 v106, v106
	v_min_f32_e32 v107, 0x42ad1f97, v107
	v_pk_mul_f32 v[98:99], v[170:171], v[98:99] op_sel_hi:[0,1]
	v_pk_mul_f32 v[96:97], v[170:171], v[96:97] op_sel_hi:[0,1]
	v_min_f32_e32 v96, 0x42ad1f97, v96
	v_min_f32_e32 v97, 0x42ad1f97, v97
	v_min_f32_e32 v98, 0x42ad1f97, v98
	v_exp_f32_e32 v107, v107
	v_or_b32_e32 v112, 16, v142
	v_exp_f32_e32 v96, v96
	v_exp_f32_e32 v97, v97
	v_exp_f32_e32 v98, v98
	v_ashrrev_i32_e32 v113, 31, v112
	v_add_f32_e32 v108, 1.0, v108
	v_add_f32_e32 v104, 1.0, v104
	v_add_f32_e32 v105, 1.0, v105
	v_add_f32_e32 v106, 1.0, v106
	v_lshlrev_b64 v[112:113], 8, v[112:113]
	v_rcp_f32_e32 v108, v108
	v_rcp_f32_e32 v104, v104
	v_rcp_f32_e32 v105, v105
	v_rcp_f32_e32 v106, v106
	v_add_f32_e32 v107, 1.0, v107
	v_cvt_pk_bf16_f32 v104, v108, v104
	v_cvt_pk_bf16_f32 v105, v105, v106
	v_cvt_pk_bf16_f32 v106, v114, v109
	v_lshl_add_u64 v[108:109], s[6:7], 0, v[112:113]
	v_rcp_f32_e32 v107, v107
	v_lshl_add_u64 v[108:109], v[108:109], 0, v[188:189]
	v_pk_mul_f32 v[102:103], v[170:171], v[102:103] op_sel_hi:[0,1]
	v_pk_mul_f32 v[100:101], v[170:171], v[100:101] op_sel_hi:[0,1]
	v_add_f32_e32 v96, 1.0, v96
	v_add_f32_e32 v97, 1.0, v97
	v_add_f32_e32 v98, 1.0, v98
	v_cvt_pk_bf16_f32 v107, v110, v107
	global_store_dwordx4 v[108:109], v[104:107], off
	v_min_f32_e32 v100, 0x42ad1f97, v100
	v_rcp_f32_e32 v104, v96
	v_min_f32_e32 v96, 0x42ad1f97, v101
	v_rcp_f32_e32 v101, v97
	v_min_f32_e32 v97, 0x42ad1f97, v102
	v_rcp_f32_e32 v102, v98
	v_min_f32_e32 v98, 0x42ad1f97, v103
	v_exp_f32_e32 v100, v100
	v_exp_f32_e32 v96, v96
	v_exp_f32_e32 v97, v97
	v_exp_f32_e32 v98, v98
	v_min_f32_e32 v99, 0x42ad1f97, v99
	v_pk_mul_f32 v[90:91], v[140:141], v[90:91] op_sel_hi:[0,1]
	v_pk_mul_f32 v[88:89], v[140:141], v[88:89] op_sel_hi:[0,1]
	v_min_f32_e32 v88, 0x42ad1f97, v88
	v_min_f32_e32 v89, 0x42ad1f97, v89
	v_min_f32_e32 v90, 0x42ad1f97, v90
	v_exp_f32_e32 v99, v99
	v_exp_f32_e32 v88, v88
	v_exp_f32_e32 v89, v89
	v_exp_f32_e32 v90, v90
	v_add_f32_e32 v100, 1.0, v100
	v_add_f32_e32 v96, 1.0, v96
	v_add_f32_e32 v97, 1.0, v97
	v_add_f32_e32 v98, 1.0, v98
	v_rcp_f32_e32 v100, v100
	v_rcp_f32_e32 v96, v96
	v_rcp_f32_e32 v97, v97
	v_rcp_f32_e32 v98, v98
	v_add_f32_e32 v99, 1.0, v99
	v_cvt_pk_bf16_f32 v96, v100, v96
	v_cvt_pk_bf16_f32 v97, v97, v98
	v_cvt_pk_bf16_f32 v98, v104, v101
	v_lshl_add_u64 v[100:101], s[30:31], 0, v[112:113]
	v_rcp_f32_e32 v99, v99
	v_lshl_add_u64 v[100:101], v[100:101], 0, v[188:189]
; __device__ __forceinline__ float sigm(float x) { x = fmaxf(x, -60.f); return __builtin_amdgcn_rcpf(1.f + __expf(-x)); }
; __device__ __forceinline__ u32x4 pack8(const f32x4& a, const f32x4& b) { u32x4 w; w.x = cvt_pk_bf16(a[0], a[1]); w.y = cvt_pk_bf16(a[2], a[3]); w.z = cvt_pk_bf16(b[0], b[1]); w.w = cvt_pk_bf16(b[2], b[3]); return w; }
; __device__ __forceinline__ size_t paddr(int row, int col) { return ((size_t)(col >> 7) * 16384 + (size_t)row) * 128 + (col & 127); }
; __device__ __forceinline__ size_t paddr(int row, int col) { return ((size_t)(col >> 7) * TH + (size_t)row) * 128 + (col & 127); }
;     template <int KIND> __device__ __forceinline__ void body(f32x4 (&acc)[2][2][4][2], const Unit& u, int wr, int wc, int fr, int fq, const Pre& pre) const {
;     ...
;         for (int ai = 0; ai < 2; ++ai)
; #pragma unroll
;             for (int m = 0; m < 4; ++m) {
;                 const int row = row0 + ai * HALF + m * 16;
;                 const float rs = rsv[ai][m];
; #pragma unroll
;                 for (int bj = 0; bj < 2; ++bj) {
;                     f32x4 v0 = acc[ai][bj][m][0] * rs, v1 = acc[ai][bj][m][1] * rs;
;                     if (KIND == 1) {
; #pragma unroll
;                         for (int j = 0; j < 4; ++j) { v0[j] = fmaxf(__log2f(1.0f - lk[bj][0][j] * sigm(-v0[j])), -120.f); v1[j] = fmaxf(__log2f(1.0f - lk[bj][1][j] * sigm(-v1[j])), -120.f); }
;                     } else if (KIND == 2) {
; #pragma unroll
;                         for (int j = 0; j < 4; ++j) { v0[j] = v0[j] * sigm(v0[j]); v1[j] = v1[j] * sigm(v1[j]); }
;                     } else if (KIND == 3) {
;                         v0 = v0 * 0.08838834764831845f; v1 = v1 * 0.08838834764831845f;
;                     } else if (KIND == 4) {
; #pragma unroll
;                         for (int j = 0; j < 4; ++j) { v0[j] = sigm(v0[j]); v1[j] = sigm(v1[j]); }
;                     }
;                     *(u32x4*)(P + paddr(row, col0 + bj * HALF)) = pack8(v0, v1);
	v_pk_mul_f32 v[94:95], v[140:141], v[94:95] op_sel_hi:[0,1]
	v_pk_mul_f32 v[92:93], v[140:141], v[92:93] op_sel_hi:[0,1]
	v_add_f32_e32 v88, 1.0, v88
	v_add_f32_e32 v89, 1.0, v89
	v_add_f32_e32 v90, 1.0, v90
	v_cvt_pk_bf16_f32 v99, v102, v99
	global_store_dwordx4 v[100:101], v[96:99], off
	v_min_f32_e32 v92, 0x42ad1f97, v92
	v_rcp_f32_e32 v98, v88
	v_min_f32_e32 v88, 0x42ad1f97, v93
	v_rcp_f32_e32 v93, v89
	v_min_f32_e32 v89, 0x42ad1f97, v94
	v_rcp_f32_e32 v94, v90
	v_min_f32_e32 v90, 0x42ad1f97, v95
	v_exp_f32_e32 v92, v92
	v_exp_f32_e32 v88, v88
	v_exp_f32_e32 v89, v89
	v_exp_f32_e32 v90, v90
	v_min_f32_e32 v91, 0x42ad1f97, v91
	v_pk_mul_f32 v[82:83], v[140:141], v[82:83] op_sel_hi:[0,1]
	v_pk_mul_f32 v[80:81], v[140:141], v[80:81] op_sel_hi:[0,1]
	v_min_f32_e32 v80, 0x42ad1f97, v80
	v_min_f32_e32 v81, 0x42ad1f97, v81
	v_min_f32_e32 v82, 0x42ad1f97, v82
	v_exp_f32_e32 v91, v91
	v_or_b32_e32 v96, 32, v142
	v_exp_f32_e32 v80, v80
	v_exp_f32_e32 v81, v81
	v_exp_f32_e32 v82, v82
	v_ashrrev_i32_e32 v97, 31, v96
	v_add_f32_e32 v92, 1.0, v92
	v_add_f32_e32 v88, 1.0, v88
	v_add_f32_e32 v89, 1.0, v89
	v_add_f32_e32 v90, 1.0, v90
	v_lshlrev_b64 v[96:97], 8, v[96:97]
	v_rcp_f32_e32 v92, v92
	v_rcp_f32_e32 v88, v88
	v_rcp_f32_e32 v89, v89
	v_rcp_f32_e32 v90, v90
	v_add_f32_e32 v91, 1.0, v91
	v_cvt_pk_bf16_f32 v88, v92, v88
	v_cvt_pk_bf16_f32 v89, v89, v90
	v_cvt_pk_bf16_f32 v90, v98, v93
	v_lshl_add_u64 v[92:93], s[6:7], 0, v[96:97]
	v_rcp_f32_e32 v91, v91
	v_lshl_add_u64 v[92:93], v[92:93], 0, v[188:189]
	v_pk_mul_f32 v[86:87], v[140:141], v[86:87] op_sel_hi:[0,1]
	v_pk_mul_f32 v[84:85], v[140:141], v[84:85] op_sel_hi:[0,1]
	v_add_f32_e32 v80, 1.0, v80
	v_add_f32_e32 v81, 1.0, v81
	v_add_f32_e32 v82, 1.0, v82
	v_cvt_pk_bf16_f32 v91, v94, v91
	global_store_dwordx4 v[92:93], v[88:91], off
	v_min_f32_e32 v84, 0x42ad1f97, v84
	v_rcp_f32_e32 v88, v80
	v_min_f32_e32 v80, 0x42ad1f97, v85
	v_rcp_f32_e32 v85, v81
	v_min_f32_e32 v81, 0x42ad1f97, v86
	v_rcp_f32_e32 v86, v82
	v_min_f32_e32 v82, 0x42ad1f97, v87
	v_exp_f32_e32 v84, v84
	v_exp_f32_e32 v80, v80
	v_exp_f32_e32 v81, v81
	v_exp_f32_e32 v82, v82
	v_min_f32_e32 v83, 0x42ad1f97, v83
	v_pk_mul_f32 v[74:75], v[138:139], v[74:75] op_sel_hi:[0,1]
	v_pk_mul_f32 v[72:73], v[138:139], v[72:73] op_sel_hi:[0,1]
	v_min_f32_e32 v72, 0x42ad1f97, v72
	v_min_f32_e32 v73, 0x42ad1f97, v73
	v_min_f32_e32 v74, 0x42ad1f97, v74
	v_exp_f32_e32 v83, v83
	v_exp_f32_e32 v72, v72
	v_exp_f32_e32 v73, v73
	v_exp_f32_e32 v74, v74
	v_add_f32_e32 v84, 1.0, v84
	v_add_f32_e32 v80, 1.0, v80
	v_add_f32_e32 v81, 1.0, v81
	v_add_f32_e32 v82, 1.0, v82
	v_rcp_f32_e32 v84, v84
	v_rcp_f32_e32 v80, v80
	v_rcp_f32_e32 v81, v81
	v_rcp_f32_e32 v82, v82
	v_add_f32_e32 v83, 1.0, v83
	v_cvt_pk_bf16_f32 v80, v84, v80
	v_cvt_pk_bf16_f32 v81, v81, v82
	v_cvt_pk_bf16_f32 v82, v88, v85
	v_lshl_add_u64 v[84:85], s[30:31], 0, v[96:97]
	v_rcp_f32_e32 v83, v83
	v_lshl_add_u64 v[84:85], v[84:85], 0, v[188:189]
	v_pk_mul_f32 v[78:79], v[138:139], v[78:79] op_sel_hi:[0,1]
	v_pk_mul_f32 v[76:77], v[138:139], v[76:77] op_sel_hi:[0,1]
	v_add_f32_e32 v72, 1.0, v72
	v_add_f32_e32 v73, 1.0, v73
	v_add_f32_e32 v74, 1.0, v74
	v_cvt_pk_bf16_f32 v83, v86, v83
	global_store_dwordx4 v[84:85], v[80:83], off
	v_min_f32_e32 v76, 0x42ad1f97, v76
	v_rcp_f32_e32 v82, v72
	v_min_f32_e32 v72, 0x42ad1f97, v77
	v_rcp_f32_e32 v77, v73
	v_min_f32_e32 v73, 0x42ad1f97, v78
	v_rcp_f32_e32 v78, v74
	v_min_f32_e32 v74, 0x42ad1f97, v79
	v_exp_f32_e32 v76, v76
	v_exp_f32_e32 v72, v72
	v_exp_f32_e32 v73, v73
	v_exp_f32_e32 v74, v74
	v_min_f32_e32 v75, 0x42ad1f97, v75
	v_pk_mul_f32 v[66:67], v[138:139], v[66:67] op_sel_hi:[0,1]
	v_pk_mul_f32 v[64:65], v[138:139], v[64:65] op_sel_hi:[0,1]
	v_min_f32_e32 v64, 0x42ad1f97, v64
	v_min_f32_e32 v65, 0x42ad1f97, v65
	v_min_f32_e32 v66, 0x42ad1f97, v66
	v_exp_f32_e32 v75, v75
	v_or_b32_e32 v80, 48, v142
	v_exp_f32_e32 v64, v64
	v_exp_f32_e32 v65, v65
	v_exp_f32_e32 v66, v66
	v_ashrrev_i32_e32 v81, 31, v80
	v_add_f32_e32 v76, 1.0, v76
	v_add_f32_e32 v72, 1.0, v72
	v_add_f32_e32 v73, 1.0, v73
	v_add_f32_e32 v74, 1.0, v74
	v_lshlrev_b64 v[80:81], 8, v[80:81]
	v_rcp_f32_e32 v76, v76
	v_rcp_f32_e32 v72, v72
	v_rcp_f32_e32 v73, v73
	v_rcp_f32_e32 v74, v74
	v_add_f32_e32 v75, 1.0, v75
	v_cvt_pk_bf16_f32 v72, v76, v72
	v_cvt_pk_bf16_f32 v73, v73, v74
	v_cvt_pk_bf16_f32 v74, v82, v77
	v_lshl_add_u64 v[76:77], s[6:7], 0, v[80:81]
	v_rcp_f32_e32 v75, v75
	v_lshl_add_u64 v[76:77], v[76:77], 0, v[188:189]
	v_pk_mul_f32 v[70:71], v[138:139], v[70:71] op_sel_hi:[0,1]
	v_pk_mul_f32 v[68:69], v[138:139], v[68:69] op_sel_hi:[0,1]
	v_add_f32_e32 v64, 1.0, v64
	v_add_f32_e32 v65, 1.0, v65
	v_add_f32_e32 v66, 1.0, v66
	v_cvt_pk_bf16_f32 v75, v78, v75
	global_store_dwordx4 v[76:77], v[72:75], off
	v_min_f32_e32 v68, 0x42ad1f97, v68
	v_rcp_f32_e32 v72, v64
	v_min_f32_e32 v64, 0x42ad1f97, v69
	v_rcp_f32_e32 v69, v65
	v_min_f32_e32 v65, 0x42ad1f97, v70
	v_rcp_f32_e32 v70, v66
	v_min_f32_e32 v66, 0x42ad1f97, v71
	v_exp_f32_e32 v68, v68
	v_exp_f32_e32 v64, v64
	v_exp_f32_e32 v65, v65
	v_exp_f32_e32 v66, v66
	v_min_f32_e32 v67, 0x42ad1f97, v67
	v_pk_mul_f32 v[58:59], v[136:137], v[58:59] op_sel_hi:[0,1]
	v_pk_mul_f32 v[56:57], v[136:137], v[56:57] op_sel_hi:[0,1]
	v_min_f32_e32 v56, 0x42ad1f97, v56
	v_min_f32_e32 v57, 0x42ad1f97, v57
	v_min_f32_e32 v58, 0x42ad1f97, v58
	v_exp_f32_e32 v67, v67
	v_exp_f32_e32 v56, v56
	v_exp_f32_e32 v57, v57
	v_exp_f32_e32 v58, v58
	v_add_f32_e32 v68, 1.0, v68
	v_add_f32_e32 v64, 1.0, v64
	v_add_f32_e32 v65, 1.0, v65
	v_add_f32_e32 v66, 1.0, v66
	v_rcp_f32_e32 v68, v68
	v_rcp_f32_e32 v64, v64
	v_rcp_f32_e32 v65, v65
	v_rcp_f32_e32 v66, v66
; __device__ __forceinline__ float sigm(float x) { x = fmaxf(x, -60.f); return __builtin_amdgcn_rcpf(1.f + __expf(-x)); }
; __device__ __forceinline__ u32x4 pack8(const f32x4& a, const f32x4& b) { u32x4 w; w.x = cvt_pk_bf16(a[0], a[1]); w.y = cvt_pk_bf16(a[2], a[3]); w.z = cvt_pk_bf16(b[0], b[1]); w.w = cvt_pk_bf16(b[2], b[3]); return w; }
; __device__ __forceinline__ size_t paddr(int row, int col) { return ((size_t)(col >> 7) * 16384 + (size_t)row) * 128 + (col & 127); }
; __device__ __forceinline__ size_t paddr(int row, int col) { return ((size_t)(col >> 7) * TH + (size_t)row) * 128 + (col & 127); }
;     template <int KIND> __device__ __forceinline__ void body(f32x4 (&acc)[2][2][4][2], const Unit& u, int wr, int wc, int fr, int fq, const Pre& pre) const {
;     ...
;         for (int ai = 0; ai < 2; ++ai)
; #pragma unroll
;             for (int m = 0; m < 4; ++m) {
;                 const int row = row0 + ai * HALF + m * 16;
;                 const float rs = rsv[ai][m];
; #pragma unroll
;                 for (int bj = 0; bj < 2; ++bj) {
;                     f32x4 v0 = acc[ai][bj][m][0] * rs, v1 = acc[ai][bj][m][1] * rs;
;                     if (KIND == 1) {
; #pragma unroll
;                         for (int j = 0; j < 4; ++j) { v0[j] = fmaxf(__log2f(1.0f - lk[bj][0][j] * sigm(-v0[j])), -120.f); v1[j] = fmaxf(__log2f(1.0f - lk[bj][1][j] * sigm(-v1[j])), -120.f); }
;                     } else if (KIND == 2) {
; #pragma unroll
;                         for (int j = 0; j < 4; ++j) { v0[j] = v0[j] * sigm(v0[j]); v1[j] = v1[j] * sigm(v1[j]); }
;                     } else if (KIND == 3) {
;                         v0 = v0 * 0.08838834764831845f; v1 = v1 * 0.08838834764831845f;
;                     } else if (KIND == 4) {
; #pragma unroll
;                         for (int j = 0; j < 4; ++j) { v0[j] = sigm(v0[j]); v1[j] = sigm(v1[j]); }
;                     }
;                     *(u32x4*)(P + paddr(row, col0 + bj * HALF)) = pack8(v0, v1);
	v_add_f32_e32 v67, 1.0, v67
	v_cvt_pk_bf16_f32 v64, v68, v64
	v_cvt_pk_bf16_f32 v65, v65, v66
	v_cvt_pk_bf16_f32 v66, v72, v69
	v_lshl_add_u64 v[68:69], s[30:31], 0, v[80:81]
	v_rcp_f32_e32 v67, v67
	v_lshl_add_u64 v[68:69], v[68:69], 0, v[188:189]
	v_pk_mul_f32 v[62:63], v[136:137], v[62:63] op_sel_hi:[0,1]
	v_pk_mul_f32 v[60:61], v[136:137], v[60:61] op_sel_hi:[0,1]
	v_add_f32_e32 v56, 1.0, v56
	v_add_f32_e32 v57, 1.0, v57
	v_add_f32_e32 v58, 1.0, v58
	v_cvt_pk_bf16_f32 v67, v70, v67
	global_store_dwordx4 v[68:69], v[64:67], off
	v_min_f32_e32 v60, 0x42ad1f97, v60
	v_rcp_f32_e32 v66, v56
	v_min_f32_e32 v56, 0x42ad1f97, v61
	v_rcp_f32_e32 v61, v57
	v_min_f32_e32 v57, 0x42ad1f97, v62
	v_rcp_f32_e32 v62, v58
	v_min_f32_e32 v58, 0x42ad1f97, v63
	v_exp_f32_e32 v60, v60
	v_exp_f32_e32 v56, v56
	v_exp_f32_e32 v57, v57
	v_exp_f32_e32 v58, v58
	v_min_f32_e32 v59, 0x42ad1f97, v59
	v_pk_mul_f32 v[50:51], v[136:137], v[50:51] op_sel_hi:[0,1]
	v_pk_mul_f32 v[48:49], v[136:137], v[48:49] op_sel_hi:[0,1]
	v_min_f32_e32 v48, 0x42ad1f97, v48
	v_min_f32_e32 v49, 0x42ad1f97, v49
	v_min_f32_e32 v50, 0x42ad1f97, v50
	v_exp_f32_e32 v59, v59
	v_exp_f32_e32 v48, v48
	v_exp_f32_e32 v49, v49
	v_exp_f32_e32 v50, v50
	v_add_f32_e32 v60, 1.0, v60
	v_add_f32_e32 v56, 1.0, v56
	v_add_f32_e32 v57, 1.0, v57
	v_add_f32_e32 v58, 1.0, v58
	v_lshl_add_u64 v[64:65], v[130:131], 0, s[94:95]
	v_rcp_f32_e32 v60, v60
	v_rcp_f32_e32 v56, v56
	v_rcp_f32_e32 v57, v57
	v_rcp_f32_e32 v58, v58
	v_add_f32_e32 v59, 1.0, v59
	v_cvt_pk_bf16_f32 v56, v60, v56
	v_cvt_pk_bf16_f32 v57, v57, v58
	v_cvt_pk_bf16_f32 v58, v66, v61
	v_lshl_add_u64 v[60:61], s[6:7], 0, v[64:65]
	v_rcp_f32_e32 v59, v59
	v_lshl_add_u64 v[60:61], v[60:61], 0, v[188:189]
	v_pk_mul_f32 v[54:55], v[136:137], v[54:55] op_sel_hi:[0,1]
	v_pk_mul_f32 v[52:53], v[136:137], v[52:53] op_sel_hi:[0,1]
	v_add_f32_e32 v48, 1.0, v48
	v_add_f32_e32 v49, 1.0, v49
	v_add_f32_e32 v50, 1.0, v50
	v_cvt_pk_bf16_f32 v59, v62, v59
	global_store_dwordx4 v[60:61], v[56:59], off
	v_min_f32_e32 v52, 0x42ad1f97, v52
	v_rcp_f32_e32 v56, v48
	v_min_f32_e32 v48, 0x42ad1f97, v53
	v_rcp_f32_e32 v53, v49
	v_min_f32_e32 v49, 0x42ad1f97, v54
	v_rcp_f32_e32 v54, v50
	v_min_f32_e32 v50, 0x42ad1f97, v55
	v_exp_f32_e32 v52, v52
	v_exp_f32_e32 v48, v48
	v_exp_f32_e32 v49, v49
	v_exp_f32_e32 v50, v50
	v_min_f32_e32 v51, 0x42ad1f97, v51
	v_pk_mul_f32 v[42:43], v[134:135], v[42:43] op_sel_hi:[0,1]
	v_pk_mul_f32 v[40:41], v[134:135], v[40:41] op_sel_hi:[0,1]
	v_min_f32_e32 v40, 0x42ad1f97, v40
	v_min_f32_e32 v41, 0x42ad1f97, v41
	v_min_f32_e32 v42, 0x42ad1f97, v42
	v_exp_f32_e32 v51, v51
	v_exp_f32_e32 v40, v40
	v_exp_f32_e32 v41, v41
	v_exp_f32_e32 v42, v42
	v_add_f32_e32 v52, 1.0, v52
	v_add_f32_e32 v48, 1.0, v48
	v_add_f32_e32 v49, 1.0, v49
	v_add_f32_e32 v50, 1.0, v50
	v_rcp_f32_e32 v52, v52
	v_rcp_f32_e32 v48, v48
	v_rcp_f32_e32 v49, v49
	v_rcp_f32_e32 v50, v50
	v_add_f32_e32 v51, 1.0, v51
	v_cvt_pk_bf16_f32 v48, v52, v48
	v_cvt_pk_bf16_f32 v49, v49, v50
	v_cvt_pk_bf16_f32 v50, v56, v53
	v_lshl_add_u64 v[52:53], s[30:31], 0, v[64:65]
	v_rcp_f32_e32 v51, v51
	v_lshl_add_u64 v[52:53], v[52:53], 0, v[188:189]
	v_pk_mul_f32 v[46:47], v[134:135], v[46:47] op_sel_hi:[0,1]
	v_pk_mul_f32 v[44:45], v[134:135], v[44:45] op_sel_hi:[0,1]
	v_add_f32_e32 v40, 1.0, v40
	v_add_f32_e32 v41, 1.0, v41
	v_add_f32_e32 v42, 1.0, v42
	v_cvt_pk_bf16_f32 v51, v54, v51
	global_store_dwordx4 v[52:53], v[48:51], off
	v_min_f32_e32 v44, 0x42ad1f97, v44
	v_rcp_f32_e32 v50, v40
	v_min_f32_e32 v40, 0x42ad1f97, v45
	v_rcp_f32_e32 v45, v41
	v_min_f32_e32 v41, 0x42ad1f97, v46
	v_rcp_f32_e32 v46, v42
	v_min_f32_e32 v42, 0x42ad1f97, v47
	v_exp_f32_e32 v44, v44
	v_exp_f32_e32 v40, v40
	v_exp_f32_e32 v41, v41
	v_exp_f32_e32 v42, v42
	v_min_f32_e32 v43, 0x42ad1f97, v43
	v_pk_mul_f32 v[34:35], v[134:135], v[34:35] op_sel_hi:[0,1]
	v_pk_mul_f32 v[32:33], v[134:135], v[32:33] op_sel_hi:[0,1]
	v_min_f32_e32 v32, 0x42ad1f97, v32
	v_min_f32_e32 v33, 0x42ad1f97, v33
	v_min_f32_e32 v34, 0x42ad1f97, v34
	v_exp_f32_e32 v43, v43
	v_exp_f32_e32 v32, v32
	v_exp_f32_e32 v33, v33
	v_exp_f32_e32 v34, v34
	v_add_f32_e32 v44, 1.0, v44
	v_add_f32_e32 v40, 1.0, v40
	v_add_f32_e32 v41, 1.0, v41
	v_add_f32_e32 v42, 1.0, v42
	v_lshl_add_u64 v[48:49], v[130:131], 0, s[96:97]
	v_rcp_f32_e32 v44, v44
	v_rcp_f32_e32 v40, v40
	v_rcp_f32_e32 v41, v41
	v_rcp_f32_e32 v42, v42
	v_add_f32_e32 v43, 1.0, v43
	v_cvt_pk_bf16_f32 v40, v44, v40
	v_cvt_pk_bf16_f32 v41, v41, v42
	v_cvt_pk_bf16_f32 v42, v50, v45
	v_lshl_add_u64 v[44:45], s[6:7], 0, v[48:49]
	v_rcp_f32_e32 v43, v43
	v_lshl_add_u64 v[44:45], v[44:45], 0, v[188:189]
	v_pk_mul_f32 v[38:39], v[134:135], v[38:39] op_sel_hi:[0,1]
	v_pk_mul_f32 v[36:37], v[134:135], v[36:37] op_sel_hi:[0,1]
	v_add_f32_e32 v32, 1.0, v32
	v_add_f32_e32 v33, 1.0, v33
	v_add_f32_e32 v34, 1.0, v34
	v_cvt_pk_bf16_f32 v43, v46, v43
	global_store_dwordx4 v[44:45], v[40:43], off
	v_min_f32_e32 v36, 0x42ad1f97, v36
	v_rcp_f32_e32 v40, v32
	v_min_f32_e32 v32, 0x42ad1f97, v37
	v_rcp_f32_e32 v37, v33
	v_min_f32_e32 v33, 0x42ad1f97, v38
	v_rcp_f32_e32 v38, v34
	v_min_f32_e32 v34, 0x42ad1f97, v39
	v_exp_f32_e32 v36, v36
	v_exp_f32_e32 v32, v32
	v_exp_f32_e32 v33, v33
	v_exp_f32_e32 v34, v34
	v_min_f32_e32 v35, 0x42ad1f97, v35
	v_pk_mul_f32 v[26:27], v[132:133], v[26:27] op_sel_hi:[0,1]
	v_pk_mul_f32 v[24:25], v[132:133], v[24:25] op_sel_hi:[0,1]
	v_min_f32_e32 v24, 0x42ad1f97, v24
	v_min_f32_e32 v25, 0x42ad1f97, v25
	v_min_f32_e32 v26, 0x42ad1f97, v26
	v_exp_f32_e32 v35, v35
	v_exp_f32_e32 v24, v24
	v_exp_f32_e32 v25, v25
	v_exp_f32_e32 v26, v26
	v_add_f32_e32 v36, 1.0, v36
	v_add_f32_e32 v32, 1.0, v32
; __device__ __forceinline__ float sigm(float x) { x = fmaxf(x, -60.f); return __builtin_amdgcn_rcpf(1.f + __expf(-x)); }
; __device__ __forceinline__ u32x4 pack8(const f32x4& a, const f32x4& b) { u32x4 w; w.x = cvt_pk_bf16(a[0], a[1]); w.y = cvt_pk_bf16(a[2], a[3]); w.z = cvt_pk_bf16(b[0], b[1]); w.w = cvt_pk_bf16(b[2], b[3]); return w; }
; __device__ __forceinline__ size_t paddr(int row, int col) { return ((size_t)(col >> 7) * 16384 + (size_t)row) * 128 + (col & 127); }
; __device__ __forceinline__ size_t paddr(int row, int col) { return ((size_t)(col >> 7) * TH + (size_t)row) * 128 + (col & 127); }
;     template <int KIND> __device__ __forceinline__ void body(f32x4 (&acc)[2][2][4][2], const Unit& u, int wr, int wc, int fr, int fq, const Pre& pre) const {
;     ...
;         for (int ai = 0; ai < 2; ++ai)
; #pragma unroll
;             for (int m = 0; m < 4; ++m) {
;                 const int row = row0 + ai * HALF + m * 16;
;                 const float rs = rsv[ai][m];
; #pragma unroll
;                 for (int bj = 0; bj < 2; ++bj) {
;                     f32x4 v0 = acc[ai][bj][m][0] * rs, v1 = acc[ai][bj][m][1] * rs;
;                     if (KIND == 1) {
; #pragma unroll
;                         for (int j = 0; j < 4; ++j) { v0[j] = fmaxf(__log2f(1.0f - lk[bj][0][j] * sigm(-v0[j])), -120.f); v1[j] = fmaxf(__log2f(1.0f - lk[bj][1][j] * sigm(-v1[j])), -120.f); }
;                     } else if (KIND == 2) {
; #pragma unroll
;                         for (int j = 0; j < 4; ++j) { v0[j] = v0[j] * sigm(v0[j]); v1[j] = v1[j] * sigm(v1[j]); }
;                     } else if (KIND == 3) {
;                         v0 = v0 * 0.08838834764831845f; v1 = v1 * 0.08838834764831845f;
;                     } else if (KIND == 4) {
; #pragma unroll
;                         for (int j = 0; j < 4; ++j) { v0[j] = sigm(v0[j]); v1[j] = sigm(v1[j]); }
;                     }
;                     *(u32x4*)(P + paddr(row, col0 + bj * HALF)) = pack8(v0, v1);
	v_add_f32_e32 v33, 1.0, v33
	v_add_f32_e32 v34, 1.0, v34
	v_rcp_f32_e32 v36, v36
	v_rcp_f32_e32 v32, v32
	v_rcp_f32_e32 v33, v33
	v_rcp_f32_e32 v34, v34
	v_add_f32_e32 v35, 1.0, v35
	v_cvt_pk_bf16_f32 v32, v36, v32
	v_cvt_pk_bf16_f32 v33, v33, v34
	v_cvt_pk_bf16_f32 v34, v40, v37
	v_lshl_add_u64 v[36:37], s[30:31], 0, v[48:49]
	v_rcp_f32_e32 v35, v35
	v_lshl_add_u64 v[36:37], v[36:37], 0, v[188:189]
	v_pk_mul_f32 v[30:31], v[132:133], v[30:31] op_sel_hi:[0,1]
	v_pk_mul_f32 v[28:29], v[132:133], v[28:29] op_sel_hi:[0,1]
	v_add_f32_e32 v24, 1.0, v24
	v_add_f32_e32 v25, 1.0, v25
	v_add_f32_e32 v26, 1.0, v26
	v_cvt_pk_bf16_f32 v35, v38, v35
	global_store_dwordx4 v[36:37], v[32:35], off
	v_min_f32_e32 v28, 0x42ad1f97, v28
	v_rcp_f32_e32 v34, v24
	v_min_f32_e32 v24, 0x42ad1f97, v29
	v_rcp_f32_e32 v29, v25
	v_min_f32_e32 v25, 0x42ad1f97, v30
	v_rcp_f32_e32 v30, v26
	v_min_f32_e32 v26, 0x42ad1f97, v31
	v_exp_f32_e32 v28, v28
	v_exp_f32_e32 v24, v24
	v_exp_f32_e32 v25, v25
	v_exp_f32_e32 v26, v26
	v_min_f32_e32 v27, 0x42ad1f97, v27
	v_pk_mul_f32 v[18:19], v[132:133], v[18:19] op_sel_hi:[0,1]
	v_pk_mul_f32 v[16:17], v[132:133], v[16:17] op_sel_hi:[0,1]
	v_min_f32_e32 v16, 0x42ad1f97, v16
	v_min_f32_e32 v17, 0x42ad1f97, v17
	v_min_f32_e32 v18, 0x42ad1f97, v18
	v_exp_f32_e32 v27, v27
	v_exp_f32_e32 v16, v16
	v_exp_f32_e32 v17, v17
	v_exp_f32_e32 v18, v18
	v_add_f32_e32 v28, 1.0, v28
	v_add_f32_e32 v24, 1.0, v24
	v_add_f32_e32 v25, 1.0, v25
	v_add_f32_e32 v26, 1.0, v26
	v_lshl_add_u64 v[32:33], v[130:131], 0, s[64:65]
	v_rcp_f32_e32 v28, v28
	v_rcp_f32_e32 v24, v24
	v_rcp_f32_e32 v25, v25
	v_rcp_f32_e32 v26, v26
	v_add_f32_e32 v27, 1.0, v27
	v_cvt_pk_bf16_f32 v24, v28, v24
	v_cvt_pk_bf16_f32 v25, v25, v26
	v_cvt_pk_bf16_f32 v26, v34, v29
	v_lshl_add_u64 v[28:29], s[6:7], 0, v[32:33]
	v_rcp_f32_e32 v27, v27
	v_lshl_add_u64 v[28:29], v[28:29], 0, v[188:189]
	v_pk_mul_f32 v[22:23], v[132:133], v[22:23] op_sel_hi:[0,1]
	v_pk_mul_f32 v[20:21], v[132:133], v[20:21] op_sel_hi:[0,1]
	v_add_f32_e32 v16, 1.0, v16
	v_add_f32_e32 v17, 1.0, v17
	v_add_f32_e32 v18, 1.0, v18
	v_cvt_pk_bf16_f32 v27, v30, v27
	global_store_dwordx4 v[28:29], v[24:27], off
	v_min_f32_e32 v20, 0x42ad1f97, v20
	v_rcp_f32_e32 v24, v16
	v_min_f32_e32 v16, 0x42ad1f97, v21
	v_rcp_f32_e32 v21, v17
	v_min_f32_e32 v17, 0x42ad1f97, v22
	v_rcp_f32_e32 v22, v18
	v_min_f32_e32 v18, 0x42ad1f97, v23
	v_exp_f32_e32 v20, v20
	v_exp_f32_e32 v16, v16
	v_exp_f32_e32 v17, v17
	v_exp_f32_e32 v18, v18
	v_min_f32_e32 v19, 0x42ad1f97, v19
	v_pk_mul_f32 v[10:11], v[128:129], v[10:11] op_sel_hi:[0,1]
	v_pk_mul_f32 v[8:9], v[128:129], v[8:9] op_sel_hi:[0,1]
	v_min_f32_e32 v8, 0x42ad1f97, v8
	v_min_f32_e32 v9, 0x42ad1f97, v9
	v_min_f32_e32 v10, 0x42ad1f97, v10
	v_exp_f32_e32 v19, v19
	v_exp_f32_e32 v8, v8
	v_exp_f32_e32 v9, v9
	v_exp_f32_e32 v10, v10
	v_add_f32_e32 v20, 1.0, v20
	v_add_f32_e32 v16, 1.0, v16
	v_add_f32_e32 v17, 1.0, v17
	v_add_f32_e32 v18, 1.0, v18
	v_rcp_f32_e32 v20, v20
	v_rcp_f32_e32 v16, v16
	v_rcp_f32_e32 v17, v17
	v_rcp_f32_e32 v18, v18
	v_add_f32_e32 v19, 1.0, v19
	v_cvt_pk_bf16_f32 v16, v20, v16
	v_cvt_pk_bf16_f32 v17, v17, v18
	v_cvt_pk_bf16_f32 v18, v24, v21
	v_lshl_add_u64 v[20:21], s[30:31], 0, v[32:33]
	v_rcp_f32_e32 v19, v19
	v_lshl_add_u64 v[20:21], v[20:21], 0, v[188:189]
	v_pk_mul_f32 v[14:15], v[128:129], v[14:15] op_sel_hi:[0,1]
	v_pk_mul_f32 v[12:13], v[128:129], v[12:13] op_sel_hi:[0,1]
	v_add_f32_e32 v8, 1.0, v8
	v_add_f32_e32 v9, 1.0, v9
	v_add_f32_e32 v10, 1.0, v10
	v_cvt_pk_bf16_f32 v19, v22, v19
	global_store_dwordx4 v[20:21], v[16:19], off
	v_min_f32_e32 v12, 0x42ad1f97, v12
	v_rcp_f32_e32 v16, v8
	v_min_f32_e32 v8, 0x42ad1f97, v13
	v_rcp_f32_e32 v13, v9
	v_min_f32_e32 v9, 0x42ad1f97, v14
	v_rcp_f32_e32 v14, v10
	v_min_f32_e32 v10, 0x42ad1f97, v15
	v_exp_f32_e32 v12, v12
	v_exp_f32_e32 v8, v8
	v_exp_f32_e32 v9, v9
	v_exp_f32_e32 v10, v10
	v_min_f32_e32 v11, 0x42ad1f97, v11
	v_pk_mul_f32 v[6:7], v[128:129], v[6:7] op_sel_hi:[0,1]
	v_pk_mul_f32 v[4:5], v[128:129], v[4:5] op_sel_hi:[0,1]
	v_pk_mul_f32 v[2:3], v[128:129], v[2:3] op_sel_hi:[0,1]
	v_pk_mul_f32 v[0:1], v[128:129], v[0:1] op_sel_hi:[0,1]
	v_min_f32_e32 v4, 0x42ad1f97, v4
	v_min_f32_e32 v0, 0x42ad1f97, v0
	v_min_f32_e32 v5, 0x42ad1f97, v5
	v_min_f32_e32 v1, 0x42ad1f97, v1
	v_min_f32_e32 v6, 0x42ad1f97, v6
	v_min_f32_e32 v2, 0x42ad1f97, v2
	v_min_f32_e32 v7, 0x42ad1f97, v7
	v_min_f32_e32 v3, 0x42ad1f97, v3
	v_exp_f32_e32 v11, v11
	v_exp_f32_e32 v4, v4
	v_exp_f32_e32 v0, v0
	v_exp_f32_e32 v5, v5
	v_exp_f32_e32 v1, v1
	v_exp_f32_e32 v6, v6
	v_exp_f32_e32 v2, v2
	v_exp_f32_e32 v7, v7
	v_exp_f32_e32 v3, v3
	v_add_f32_e32 v12, 1.0, v12
	v_add_f32_e32 v8, 1.0, v8
	v_add_f32_e32 v9, 1.0, v9
	v_add_f32_e32 v10, 1.0, v10
	v_lshl_add_u64 v[176:177], v[130:131], 0, s[82:83]
	v_rcp_f32_e32 v12, v12
	v_rcp_f32_e32 v8, v8
	v_rcp_f32_e32 v9, v9
	v_rcp_f32_e32 v10, v10
	v_add_f32_e32 v11, 1.0, v11
	v_cvt_pk_bf16_f32 v8, v12, v8
	v_cvt_pk_bf16_f32 v9, v9, v10
	v_cvt_pk_bf16_f32 v10, v16, v13
	v_lshl_add_u64 v[12:13], s[6:7], 0, v[176:177]
	v_rcp_f32_e32 v11, v11
	v_lshl_add_u64 v[12:13], v[12:13], 0, v[188:189]
	v_add_f32_e32 v4, 1.0, v4
	v_add_f32_e32 v0, 1.0, v0
	v_add_f32_e32 v5, 1.0, v5
	v_add_f32_e32 v1, 1.0, v1
	v_add_f32_e32 v6, 1.0, v6
	v_add_f32_e32 v2, 1.0, v2
	v_add_f32_e32 v7, 1.0, v7
	v_add_f32_e32 v3, 1.0, v3
	v_mov_b64_e32 v[132:133], s[8:9]
	v_cvt_pk_bf16_f32 v11, v14, v11
	global_store_dwordx4 v[12:13], v[8:11], off
	v_rcp_f32_e32 v4, v4
	v_rcp_f32_e32 v0, v0
	v_rcp_f32_e32 v5, v5
	v_rcp_f32_e32 v1, v1
	v_rcp_f32_e32 v6, v6
	v_rcp_f32_e32 v2, v2
	v_rcp_f32_e32 v7, v7
	v_rcp_f32_e32 v3, v3
	v_cvt_pk_bf16_f32 v128, v4, v5
	v_cvt_pk_bf16_f32 v129, v6, v7
	v_cvt_pk_bf16_f32 v130, v0, v1
	v_cvt_pk_bf16_f32 v131, v2, v3
